# post_tile head-norm loop: the four row loads of each unrolled iteration issued up front
# baseline (speedup 1.0000x reference)
.LBB0_287:
	v_add_u32_e32 v104, s0, v43
	v_mul_hi_i32 v105, v104, s97
	v_lshrrev_b32_e32 v106, 31, v105
	v_ashrrev_i32_e32 v105, 1, v105
	v_add_u32_e32 v105, v105, v106
	v_mul_lo_u32 v106, v105, 12
	v_sub_u32_e32 v106, v104, v106
	v_cmp_lt_i32_e64 s[54:55], 7, v106
	v_cmp_lt_i32_e64 s[56:57], 9, v106
	v_lshlrev_b32_e32 v108, 6, v106
	v_add_u32_e32 v107, s12, v105
	v_cndmask_b32_e64 v110, 0, 4, s[54:55]
	v_cndmask_b32_e64 v111, 0, 2, s[56:57]
	v_mov_b64_e32 v[112:113], s[10:11]
	v_add_u32_e32 v110, v110, v111
	v_mad_i64_i32 v[112:113], s[52:53], v107, s23, v[112:113]
	v_lshl_add_u32 v108, v110, 6, v108
	v_mov_b32_e32 v109, 0
	v_lshl_add_u64 v[108:109], v[108:109], 1, v[112:113]
	v_lshl_add_u64 v[108:109], v[108:109], 0, v[0:1]
	global_load_dwordx4 v[88:91], v[108:109], off
	v_add_u32_e32 v104, 64, v104
	v_mul_hi_i32 v105, v104, s97
	v_lshrrev_b32_e32 v106, 31, v105
	v_ashrrev_i32_e32 v105, 1, v105
	v_add_u32_e32 v105, v105, v106
	v_mul_lo_u32 v106, v105, 12
	v_sub_u32_e32 v106, v104, v106
	v_cmp_lt_i32_e64 s[54:55], 7, v106
	v_cmp_lt_i32_e64 s[56:57], 9, v106
	v_lshlrev_b32_e32 v108, 6, v106
	v_add_u32_e32 v107, s12, v105
	v_cndmask_b32_e64 v110, 0, 4, s[54:55]
	v_cndmask_b32_e64 v111, 0, 2, s[56:57]
	v_mov_b64_e32 v[112:113], s[10:11]
	v_add_u32_e32 v110, v110, v111
	v_mad_i64_i32 v[112:113], s[52:53], v107, s23, v[112:113]
	v_lshl_add_u32 v108, v110, 6, v108
	v_mov_b32_e32 v109, 0
	v_lshl_add_u64 v[108:109], v[108:109], 1, v[112:113]
	v_lshl_add_u64 v[108:109], v[108:109], 0, v[0:1]
	global_load_dwordx4 v[92:95], v[108:109], off
	v_add_u32_e32 v104, 64, v104
	v_mul_hi_i32 v105, v104, s97
	v_lshrrev_b32_e32 v106, 31, v105
	v_ashrrev_i32_e32 v105, 1, v105
	v_add_u32_e32 v105, v105, v106
	v_mul_lo_u32 v106, v105, 12
	v_sub_u32_e32 v106, v104, v106
	v_cmp_lt_i32_e64 s[54:55], 7, v106
	v_cmp_lt_i32_e64 s[56:57], 9, v106
	v_lshlrev_b32_e32 v108, 6, v106
	v_add_u32_e32 v107, s12, v105
	v_cndmask_b32_e64 v110, 0, 4, s[54:55]
	v_cndmask_b32_e64 v111, 0, 2, s[56:57]
	v_mov_b64_e32 v[112:113], s[10:11]
	v_add_u32_e32 v110, v110, v111
	v_mad_i64_i32 v[112:113], s[52:53], v107, s23, v[112:113]
	v_lshl_add_u32 v108, v110, 6, v108
	v_mov_b32_e32 v109, 0
	v_lshl_add_u64 v[108:109], v[108:109], 1, v[112:113]
	v_lshl_add_u64 v[108:109], v[108:109], 0, v[0:1]
	global_load_dwordx4 v[96:99], v[108:109], off
	v_add_u32_e32 v104, 64, v104
	v_mul_hi_i32 v105, v104, s97
	v_lshrrev_b32_e32 v106, 31, v105
	v_ashrrev_i32_e32 v105, 1, v105
	v_add_u32_e32 v105, v105, v106
	v_mul_lo_u32 v106, v105, 12
	v_sub_u32_e32 v106, v104, v106
	v_cmp_lt_i32_e64 s[54:55], 7, v106
	v_cmp_lt_i32_e64 s[56:57], 9, v106
	v_lshlrev_b32_e32 v108, 6, v106
	v_add_u32_e32 v107, s12, v105
	v_cndmask_b32_e64 v110, 0, 4, s[54:55]
	v_cndmask_b32_e64 v111, 0, 2, s[56:57]
	v_mov_b64_e32 v[112:113], s[10:11]
	v_add_u32_e32 v110, v110, v111
	v_mad_i64_i32 v[112:113], s[52:53], v107, s23, v[112:113]
	v_lshl_add_u32 v108, v110, 6, v108
	v_mov_b32_e32 v109, 0
	v_lshl_add_u64 v[108:109], v[108:109], 1, v[112:113]
	v_lshl_add_u64 v[108:109], v[108:109], 0, v[0:1]
	global_load_dwordx4 v[100:103], v[108:109], off
	v_add_u32_e32 v53, s0, v43
	v_mul_hi_i32 v26, v53, s97
	v_lshrrev_b32_e32 v27, 31, v26
	v_ashrrev_i32_e32 v26, 1, v26
	v_add_u32_e32 v27, v26, v27
	v_mul_lo_u32 v26, v27, 12
	v_sub_u32_e32 v32, v53, v26
	v_cmp_gt_i32_e64 s[44:45], 8, v32
	v_cmp_lt_i32_e64 s[46:47], 7, v32
	v_lshlrev_b32_e32 v26, 6, v32
	s_and_saveexec_b64 s[2:3], s[46:47]
	s_xor_b64 s[2:3], exec, s[2:3]
	s_cbranch_execz .LBB0_293
	v_cmp_lt_u32_e32 vcc, 9, v32
	v_lshlrev_b32_e32 v28, 6, v32
	s_and_saveexec_b64 s[8:9], vcc
	s_xor_b64 s[8:9], exec, s[8:9]
	v_add_u32_e32 v30, 0x180, v28
	s_andn2_saveexec_b64 s[8:9], s[8:9]
	v_add_u32_e32 v30, 0x100, v28
	s_or_b64 exec, exec, s[8:9]
.LBB0_293:
	s_andn2_saveexec_b64 s[2:3], s[2:3]
	v_mov_b32_e32 v30, v26
	s_or_b64 exec, exec, s[2:3]
	v_add_u32_e32 v28, s12, v27
	v_mov_b64_e32 v[54:55], s[10:11]
	v_mad_i64_i32 v[54:55], s[2:3], v28, s23, v[54:55]
	v_ashrrev_i32_e32 v31, 31, v30
	v_lshl_add_u64 v[30:31], v[30:31], 1, v[54:55]
	v_lshl_add_u64 v[30:31], v[30:31], 0, v[0:1]
	v_lshl_add_u32 v27, v27, 5, 0
	v_cmp_lt_i32_e64 s[50:51], 0, v62
	s_waitcnt vmcnt(3)
	v_mov_b32_e32 v82, v88
	v_mov_b32_e32 v83, v89
	v_mov_b32_e32 v84, v90
	v_mov_b32_e32 v85, v91
	v_and_b32_e32 v60, 0xffff0000, v82
	v_lshlrev_b32_e32 v29, 16, v82
	v_mul_f32_e32 v33, v60, v60
	v_lshlrev_b32_e32 v57, 16, v83
	v_fmac_f32_e32 v33, v29, v29
	v_and_b32_e32 v56, 0xffff0000, v83
	v_fmac_f32_e32 v33, v57, v57
	v_lshlrev_b32_e32 v54, 16, v84
	v_fmac_f32_e32 v33, v56, v56
	v_and_b32_e32 v55, 0xffff0000, v84
	v_and_b32_e32 v58, 0xffff0000, v85
	v_lshlrev_b32_e32 v59, 16, v85
	v_fmac_f32_e32 v33, v54, v54
	v_pk_mul_f32 v[30:31], v[58:59], v[58:59]
	v_fmac_f32_e32 v33, v55, v55
	v_add_f32_e32 v31, v31, v33
	v_add_f32_e32 v30, v30, v31
	ds_bpermute_b32 v31, v65, v30
	s_waitcnt lgkmcnt(0)
	v_add_f32_e32 v30, v30, v31
	ds_bpermute_b32 v31, v66, v30
	s_waitcnt lgkmcnt(0)
	v_add_f32_e32 v30, v30, v31
	ds_bpermute_b32 v31, v67, v30
	s_waitcnt lgkmcnt(0)
	v_add_f32_e32 v30, v30, v31
	v_fmamk_f32 v30, v30, 0x3c800000, v188
	v_mul_f32_e32 v31, 0x4f800000, v30
	v_cmp_gt_f32_e32 vcc, s66, v30
	s_nop 1
	v_cndmask_b32_e32 v30, v30, v31, vcc
	v_sqrt_f32_e32 v31, v30
	s_nop 0
	v_add_u32_e32 v33, -1, v31
	v_add_u32_e32 v61, 1, v31
	v_fma_f32 v82, -v33, v31, v30
	v_fma_f32 v83, -v61, v31, v30
	v_cmp_ge_f32_e64 s[48:49], 0, v82
	s_nop 1
	v_cndmask_b32_e64 v31, v31, v33, s[48:49]
	v_cmp_lt_f32_e64 s[48:49], 0, v83
	s_nop 1
	v_cndmask_b32_e64 v31, v31, v61, s[48:49]
	v_mul_f32_e32 v33, 0x37800000, v31
	v_cndmask_b32_e32 v31, v31, v33, vcc
	v_cmp_class_f32_e32 vcc, v30, v192
	v_cmp_gt_u32_e64 s[48:49], 10, v32
	s_nop 0
	v_cndmask_b32_e32 v30, v31, v30, vcc
	v_div_scale_f32 v31, s[2:3], v30, v30, 1.0
	v_rcp_f32_e32 v33, v31
	v_div_scale_f32 v61, vcc, 1.0, v30, 1.0
	v_cndmask_b32_e64 v82, v18, v10, s[48:49]
	v_fma_f32 v83, -v31, v33, 1.0
	v_fmac_f32_e32 v33, v83, v33
	v_mul_f32_e32 v83, v61, v33
	v_fma_f32 v84, -v31, v83, v61
	v_fmac_f32_e32 v83, v84, v33
	v_fma_f32 v31, -v31, v83, v61
	v_div_fmas_f32 v31, v31, v33, v83
	v_div_fixup_f32 v61, v31, v30, 1.0
	v_mul_f32_e32 v29, v61, v29
	v_cndmask_b32_e64 v30, v82, v2, s[44:45]
	v_mul_f32_e32 v30, v30, v29
	ds_bpermute_b32 v31, v65, v30
	v_cmp_lt_u32_e32 vcc, 9, v32
	ds_read2st64_b32 v[32:33], v27 offset1:8
	v_ashrrev_i32_e32 v29, 31, v28
	s_and_saveexec_b64 s[2:3], s[50:51]
	s_xor_b64 s[2:3], exec, s[2:3]
	s_cbranch_execz .LBB0_299
	v_cmp_eq_u32_e64 s[50:51], 1, v62
	s_and_saveexec_b64 s[8:9], s[50:51]
	s_cbranch_execz .LBB0_298
	s_waitcnt lgkmcnt(0)
	v_mov_b32_e32 v82, v33
	v_mov_b32_e32 v83, v32
	v_mov_b32_e32 v32, v31
	v_mov_b32_e32 v33, v30
	v_pk_mul_f32 v[30:31], v[82:83], v[32:33]
	s_nop 0
	v_add_f32_e32 v30, v30, v31

.LBB0_357:
	s_andn2_saveexec_b64 s[2:3], s[2:3]
	v_mov_b32_e32 v30, v26
	s_or_b64 exec, exec, s[2:3]
	v_add_u32_e32 v28, s12, v27
	v_mov_b64_e32 v[54:55], s[10:11]
	v_mad_i64_i32 v[54:55], s[2:3], v28, s23, v[54:55]
	v_ashrrev_i32_e32 v31, 31, v30
	v_lshl_add_u64 v[30:31], v[30:31], 1, v[54:55]
	v_lshl_add_u64 v[30:31], v[30:31], 0, v[0:1]
	v_lshl_add_u32 v27, v27, 5, 0
	v_cmp_lt_i32_e64 s[50:51], 0, v62
	s_waitcnt vmcnt(3)
	v_mov_b32_e32 v56, v92
	v_mov_b32_e32 v57, v93
	v_mov_b32_e32 v58, v94
	v_mov_b32_e32 v59, v95
	v_and_b32_e32 v82, 0xffff0000, v56
	v_lshlrev_b32_e32 v29, 16, v56
	v_mul_f32_e32 v32, v82, v82
	v_lshlrev_b32_e32 v61, 16, v57
	v_fmac_f32_e32 v32, v29, v29
	v_and_b32_e32 v60, 0xffff0000, v57
	v_fmac_f32_e32 v32, v61, v61
	v_lshlrev_b32_e32 v57, 16, v58
	v_fmac_f32_e32 v32, v60, v60
	v_and_b32_e32 v56, 0xffff0000, v58
	v_and_b32_e32 v58, 0xffff0000, v59
	v_lshlrev_b32_e32 v59, 16, v59
	v_fmac_f32_e32 v32, v57, v57
	v_pk_mul_f32 v[30:31], v[58:59], v[58:59]
	v_fmac_f32_e32 v32, v56, v56
	v_add_f32_e32 v31, v31, v32
	v_add_f32_e32 v30, v30, v31
	ds_bpermute_b32 v31, v65, v30
	s_waitcnt lgkmcnt(0)
	v_add_f32_e32 v30, v30, v31
	ds_bpermute_b32 v31, v66, v30
	s_waitcnt lgkmcnt(0)
	v_add_f32_e32 v30, v30, v31
	ds_bpermute_b32 v31, v67, v30
	s_waitcnt lgkmcnt(0)
	v_add_f32_e32 v30, v30, v31
	v_fmamk_f32 v30, v30, 0x3c800000, v188
	v_mul_f32_e32 v31, 0x4f800000, v30
	v_cmp_gt_f32_e32 vcc, s66, v30
	s_nop 1
	v_cndmask_b32_e32 v30, v30, v31, vcc
	v_sqrt_f32_e32 v31, v30
	s_nop 0
	v_add_u32_e32 v32, -1, v31
	v_add_u32_e32 v54, 1, v31
	v_fma_f32 v55, -v32, v31, v30
	v_fma_f32 v83, -v54, v31, v30
	v_cmp_ge_f32_e64 s[48:49], 0, v55
	s_nop 1
	v_cndmask_b32_e64 v31, v31, v32, s[48:49]
	v_cmp_lt_f32_e64 s[48:49], 0, v83
	s_nop 1
	v_cndmask_b32_e64 v31, v31, v54, s[48:49]
	v_mul_f32_e32 v32, 0x37800000, v31
	v_cndmask_b32_e32 v31, v31, v32, vcc
	v_cmp_class_f32_e32 vcc, v30, v192
	v_cmp_gt_u32_e64 s[48:49], 10, v33
	s_nop 0
	v_cndmask_b32_e32 v30, v31, v30, vcc
	v_div_scale_f32 v31, s[2:3], v30, v30, 1.0
	v_rcp_f32_e32 v32, v31
	v_div_scale_f32 v55, vcc, 1.0, v30, 1.0
	v_cndmask_b32_e64 v54, v18, v10, s[48:49]
	v_fma_f32 v83, -v31, v32, 1.0
	v_fmac_f32_e32 v32, v83, v32
	v_mul_f32_e32 v83, v55, v32
	v_fma_f32 v84, -v31, v83, v55
	v_fmac_f32_e32 v83, v84, v32
	v_fma_f32 v31, -v31, v83, v55
	v_div_fmas_f32 v31, v31, v32, v83
	v_div_fixup_f32 v83, v31, v30, 1.0
	v_mul_f32_e32 v29, v83, v29
	v_cndmask_b32_e64 v30, v54, v2, s[44:45]
	v_mul_f32_e32 v30, v30, v29
	ds_bpermute_b32 v32, v65, v30
	ds_read2st64_b32 v[54:55], v27 offset1:8
	v_ashrrev_i32_e32 v29, 31, v28
	v_cmp_lt_u32_e32 vcc, 9, v33
	s_and_saveexec_b64 s[2:3], s[50:51]
	s_xor_b64 s[2:3], exec, s[2:3]
	s_cbranch_execz .LBB0_363
	v_cmp_eq_u32_e64 s[50:51], 1, v62
	s_and_saveexec_b64 s[8:9], s[50:51]
	s_cbranch_execz .LBB0_362
	s_waitcnt lgkmcnt(0)
	v_mov_b32_e32 v84, v55
	v_mov_b32_e32 v85, v54
	v_mov_b32_e32 v33, v30
	v_pk_mul_f32 v[30:31], v[84:85], v[32:33]
	s_nop 0
	v_add_f32_e32 v30, v30, v31

.LBB0_421:
	s_andn2_saveexec_b64 s[2:3], s[2:3]
	v_mov_b32_e32 v30, v26
	s_or_b64 exec, exec, s[2:3]
	v_add_u32_e32 v28, s12, v27
	v_mov_b64_e32 v[54:55], s[10:11]
	v_mad_i64_i32 v[54:55], s[2:3], v28, s23, v[54:55]
	v_ashrrev_i32_e32 v31, 31, v30
	v_lshl_add_u64 v[30:31], v[30:31], 1, v[54:55]
	v_lshl_add_u64 v[30:31], v[30:31], 0, v[0:1]
	v_lshl_add_u32 v27, v27, 5, 0
	v_cmp_lt_i32_e64 s[50:51], 0, v62
	s_waitcnt vmcnt(3)
	v_mov_b32_e32 v56, v96
	v_mov_b32_e32 v57, v97
	v_mov_b32_e32 v58, v98
	v_mov_b32_e32 v59, v99
	v_and_b32_e32 v82, 0xffff0000, v56
	v_lshlrev_b32_e32 v29, 16, v56
	v_mul_f32_e32 v32, v82, v82
	v_lshlrev_b32_e32 v61, 16, v57
	v_fmac_f32_e32 v32, v29, v29
	v_and_b32_e32 v60, 0xffff0000, v57
	v_fmac_f32_e32 v32, v61, v61
	v_lshlrev_b32_e32 v57, 16, v58
	v_fmac_f32_e32 v32, v60, v60
	v_and_b32_e32 v56, 0xffff0000, v58
	v_and_b32_e32 v58, 0xffff0000, v59
	v_lshlrev_b32_e32 v59, 16, v59
	v_fmac_f32_e32 v32, v57, v57
	v_pk_mul_f32 v[30:31], v[58:59], v[58:59]
	v_fmac_f32_e32 v32, v56, v56
	v_add_f32_e32 v31, v31, v32
	v_add_f32_e32 v30, v30, v31
	ds_bpermute_b32 v31, v65, v30
	s_waitcnt lgkmcnt(0)
	v_add_f32_e32 v30, v30, v31
	ds_bpermute_b32 v31, v66, v30
	s_waitcnt lgkmcnt(0)
	v_add_f32_e32 v30, v30, v31
	ds_bpermute_b32 v31, v67, v30
	s_waitcnt lgkmcnt(0)
	v_add_f32_e32 v30, v30, v31
	v_fmamk_f32 v30, v30, 0x3c800000, v188
	v_mul_f32_e32 v31, 0x4f800000, v30
	v_cmp_gt_f32_e32 vcc, s66, v30
	s_nop 1
	v_cndmask_b32_e32 v30, v30, v31, vcc
	v_sqrt_f32_e32 v31, v30
	s_nop 0
	v_add_u32_e32 v32, -1, v31
	v_add_u32_e32 v54, 1, v31
	v_fma_f32 v55, -v32, v31, v30
	v_fma_f32 v83, -v54, v31, v30
	v_cmp_ge_f32_e64 s[48:49], 0, v55
	s_nop 1
	v_cndmask_b32_e64 v31, v31, v32, s[48:49]
	v_cmp_lt_f32_e64 s[48:49], 0, v83
	s_nop 1
	v_cndmask_b32_e64 v31, v31, v54, s[48:49]
	v_mul_f32_e32 v32, 0x37800000, v31
	v_cndmask_b32_e32 v31, v31, v32, vcc
	v_cmp_class_f32_e32 vcc, v30, v192
	v_cmp_gt_u32_e64 s[48:49], 10, v33
	s_nop 0
	v_cndmask_b32_e32 v30, v31, v30, vcc
	v_div_scale_f32 v31, s[2:3], v30, v30, 1.0
	v_rcp_f32_e32 v32, v31
	v_div_scale_f32 v55, vcc, 1.0, v30, 1.0
	v_cndmask_b32_e64 v54, v18, v10, s[48:49]
	v_fma_f32 v83, -v31, v32, 1.0
	v_fmac_f32_e32 v32, v83, v32
	v_mul_f32_e32 v83, v55, v32
	v_fma_f32 v84, -v31, v83, v55
	v_fmac_f32_e32 v83, v84, v32
	v_fma_f32 v31, -v31, v83, v55
	v_div_fmas_f32 v31, v31, v32, v83
	v_div_fixup_f32 v83, v31, v30, 1.0
	v_mul_f32_e32 v29, v83, v29
	v_cndmask_b32_e64 v30, v54, v2, s[44:45]
	v_mul_f32_e32 v30, v30, v29
	ds_bpermute_b32 v32, v65, v30
	ds_read2st64_b32 v[54:55], v27 offset1:8
	v_ashrrev_i32_e32 v29, 31, v28
	v_cmp_lt_u32_e32 vcc, 9, v33
	s_and_saveexec_b64 s[2:3], s[50:51]
	s_xor_b64 s[2:3], exec, s[2:3]
	s_cbranch_execz .LBB0_427
	v_cmp_eq_u32_e64 s[50:51], 1, v62
	s_and_saveexec_b64 s[8:9], s[50:51]
	s_cbranch_execz .LBB0_426
	s_waitcnt lgkmcnt(0)
	v_mov_b32_e32 v84, v55
	v_mov_b32_e32 v85, v54
	v_mov_b32_e32 v33, v30
	v_pk_mul_f32 v[30:31], v[84:85], v[32:33]
	s_nop 0
	v_add_f32_e32 v30, v30, v31

.LBB0_485:
	s_andn2_saveexec_b64 s[2:3], s[2:3]
	v_mov_b32_e32 v30, v26
	s_or_b64 exec, exec, s[2:3]
	v_add_u32_e32 v28, s12, v27
	v_mov_b64_e32 v[54:55], s[10:11]
	v_mad_i64_i32 v[54:55], s[2:3], v28, s23, v[54:55]
	v_ashrrev_i32_e32 v31, 31, v30
	v_lshl_add_u64 v[30:31], v[30:31], 1, v[54:55]
	v_lshl_add_u64 v[30:31], v[30:31], 0, v[0:1]
	v_lshl_add_u32 v27, v27, 5, 0
	v_cmp_lt_i32_e64 s[50:51], 0, v62
	s_waitcnt vmcnt(3)
	v_mov_b32_e32 v56, v100
	v_mov_b32_e32 v57, v101
	v_mov_b32_e32 v58, v102
	v_mov_b32_e32 v59, v103
	v_and_b32_e32 v61, 0xffff0000, v56
	v_lshlrev_b32_e32 v29, 16, v56
	v_mul_f32_e32 v32, v61, v61
	v_lshlrev_b32_e32 v60, 16, v57
	v_fmac_f32_e32 v32, v29, v29
	v_and_b32_e32 v57, 0xffff0000, v57
	v_fmac_f32_e32 v32, v60, v60
	v_lshlrev_b32_e32 v56, 16, v58
	v_fmac_f32_e32 v32, v57, v57
	v_and_b32_e32 v53, 0xffff0000, v58
	v_and_b32_e32 v58, 0xffff0000, v59
	v_lshlrev_b32_e32 v59, 16, v59
	v_fmac_f32_e32 v32, v56, v56
	v_pk_mul_f32 v[30:31], v[58:59], v[58:59]
	v_fmac_f32_e32 v32, v53, v53
	v_add_f32_e32 v31, v31, v32
	v_add_f32_e32 v30, v30, v31
	ds_bpermute_b32 v31, v65, v30
	s_waitcnt lgkmcnt(0)
	v_add_f32_e32 v30, v30, v31
	ds_bpermute_b32 v31, v66, v30
	s_waitcnt lgkmcnt(0)
	v_add_f32_e32 v30, v30, v31
	ds_bpermute_b32 v31, v67, v30
	s_waitcnt lgkmcnt(0)
	v_add_f32_e32 v30, v30, v31
	v_fmamk_f32 v30, v30, 0x3c800000, v188
	v_mul_f32_e32 v31, 0x4f800000, v30
	v_cmp_gt_f32_e32 vcc, s66, v30
	s_nop 1
	v_cndmask_b32_e32 v30, v30, v31, vcc
	v_sqrt_f32_e32 v31, v30
	s_nop 0
	v_add_u32_e32 v32, -1, v31
	v_add_u32_e32 v54, 1, v31
	v_fma_f32 v55, -v32, v31, v30
	v_fma_f32 v82, -v54, v31, v30
	v_cmp_ge_f32_e64 s[48:49], 0, v55
	s_nop 1
	v_cndmask_b32_e64 v31, v31, v32, s[48:49]
	v_cmp_lt_f32_e64 s[48:49], 0, v82
	s_nop 1
	v_cndmask_b32_e64 v31, v31, v54, s[48:49]
	v_mul_f32_e32 v32, 0x37800000, v31
	v_cndmask_b32_e32 v31, v31, v32, vcc
	v_cmp_class_f32_e32 vcc, v30, v192
	v_cmp_gt_u32_e64 s[48:49], 10, v33
	s_nop 0
	v_cndmask_b32_e32 v30, v31, v30, vcc
	v_div_scale_f32 v31, s[2:3], v30, v30, 1.0
	v_rcp_f32_e32 v32, v31
	v_div_scale_f32 v55, vcc, 1.0, v30, 1.0
	v_cndmask_b32_e64 v54, v18, v10, s[48:49]
	v_fma_f32 v82, -v31, v32, 1.0
	v_fmac_f32_e32 v32, v82, v32
	v_mul_f32_e32 v82, v55, v32
	v_fma_f32 v83, -v31, v82, v55
	v_fmac_f32_e32 v82, v83, v32
	v_fma_f32 v31, -v31, v82, v55
	v_div_fmas_f32 v31, v31, v32, v82
	v_div_fixup_f32 v82, v31, v30, 1.0
	v_mul_f32_e32 v29, v82, v29
	v_cndmask_b32_e64 v30, v54, v2, s[44:45]
	v_mul_f32_e32 v30, v30, v29
	ds_bpermute_b32 v32, v65, v30
	ds_read2st64_b32 v[54:55], v27 offset1:8
	v_ashrrev_i32_e32 v29, 31, v28
	v_cmp_lt_u32_e32 vcc, 9, v33
	s_and_saveexec_b64 s[2:3], s[50:51]
	s_xor_b64 s[2:3], exec, s[2:3]
	s_cbranch_execz .LBB0_491
	v_cmp_eq_u32_e64 s[50:51], 1, v62
	s_and_saveexec_b64 s[8:9], s[50:51]
	s_cbranch_execz .LBB0_490
	s_waitcnt lgkmcnt(0)
	v_mov_b32_e32 v84, v55
	v_mov_b32_e32 v85, v54
	v_mov_b32_e32 v33, v30
	v_pk_mul_f32 v[30:31], v[84:85], v[32:33]
	s_nop 0
	v_add_f32_e32 v30, v30, v31
